# strategy #2 prologue de-serialisation: attn_shift max|gain| scans at the head of the dil and swa phases (8-trip loops with vmcnt(0) per trip) replaced by one dword per lane + DPP/readlane wave max
# speedup vs baseline: 1.0049x; 1.0049x over previous
.LBB0_478:
	v_readlane_b32 s4, v254, 9
	s_cmp_lt_i32 s4, 3
	s_cselect_b64 s[2:3], -1, 0
	s_and_b64 s[0:1], s[2:3], s[0:1]
	s_andn2_b64 vcc, exec, s[0:1]
	v_readlane_b32 s5, v254, 10
	v_readlane_b32 s6, v254, 11
	v_readlane_b32 s7, v254, 12
	s_cbranch_vccnz .LBB0_515
	v_writelane_b32 v254, s0, 33
	s_waitcnt lgkmcnt(0)
	s_add_u32 s78, s96, 0x5500000
	s_addc_u32 s79, s97, 0
	v_writelane_b32 v254, s1, 34
	v_writelane_b32 v254, s89, 35
	s_mov_b32 s0, s88
	s_mov_b64 s[20:21], s[90:91]
	v_writelane_b32 v254, s0, 36
	s_cmpk_gt_i32 s88, 0x5ff
	s_nop 0
	v_writelane_b32 v254, s1, 37
	s_cbranch_scc1 .LBB0_511
	v_lshlrev_b32_e32 v0, 2, v227
	global_load_dword v8, v0, s[74:75]
	global_load_dword v9, v0, s[76:77]
	s_waitcnt vmcnt(0) lgkmcnt(0)
	v_and_b32_e32 v8, 0x7fffffff, v8
	v_and_b32_e32 v9, 0x7fffffff, v9
	s_nop 1
	v_max_f32_dpp v8, v8, v8 quad_perm:[1,0,3,2] row_mask:0xf bank_mask:0xf
	v_max_f32_dpp v9, v9, v9 quad_perm:[1,0,3,2] row_mask:0xf bank_mask:0xf
	s_nop 1
	v_max_f32_dpp v8, v8, v8 quad_perm:[2,3,0,1] row_mask:0xf bank_mask:0xf
	v_max_f32_dpp v9, v9, v9 quad_perm:[2,3,0,1] row_mask:0xf bank_mask:0xf
	s_nop 1
	v_max_f32_dpp v8, v8, v8 row_half_mirror row_mask:0xf bank_mask:0xf
	v_max_f32_dpp v9, v9, v9 row_half_mirror row_mask:0xf bank_mask:0xf
	s_nop 1
	v_max_f32_dpp v8, v8, v8 row_mirror row_mask:0xf bank_mask:0xf
	v_max_f32_dpp v9, v9, v9 row_mirror row_mask:0xf bank_mask:0xf
	s_nop 1
	v_readlane_b32 s0, v8, 0
	v_readlane_b32 s1, v8, 16
	v_readlane_b32 s2, v8, 32
	v_readlane_b32 s3, v8, 48
	s_max_u32 s0, s0, s1
	s_max_u32 s2, s2, s3
	s_max_u32 s0, s0, s2
	v_readlane_b32 s1, v9, 0
	v_readlane_b32 s2, v9, 16
	v_readlane_b32 s3, v9, 32
	v_readlane_b32 s98, v9, 48
	s_max_u32 s1, s1, s2
	s_max_u32 s3, s3, s98
	s_max_u32 s1, s1, s3
	s_nop 0
	v_mov_b32_e32 v8, s0
	v_mov_b32_e32 v9, s1
	v_readlane_b32 s0, v254, 36
	v_readlane_b32 s1, v254, 37
	s_mov_b32 s2, s0
	s_mul_hi_i32 s0, s0, 0x55555556
	s_lshr_b32 s1, s0, 31
	s_add_i32 s0, s0, s1
	s_mul_i32 s1, s0, 3
	s_sub_i32 s76, s2, s1
	s_ashr_i32 s94, s0, 7
	s_bfe_u32 s92, s0, 0x30004
	s_and_b32 s0, s0, 15
	s_lshl_b32 s8, s76, 1
	s_lshr_b32 s93, s0, s8
	s_lshl_b32 s1, -1, s8
	s_lshl_b32 s14, s93, 8
	s_ashr_i32 s95, s94, 31
	v_lshlrev_b32_e32 v0, 3, v226
	s_andn2_b32 s77, s0, s1
	s_lshl_b64 s[0:1], s[94:95], 12
	s_add_i32 s15, s14, 0xffffff80
	v_and_b32_e32 v0, 56, v0
	v_mov_b32_e32 v96, 0
	s_mov_b32 s9, 0
	s_cmp_eq_u32 s93, 0
	v_lshlrev_b32_e32 v180, 1, v0
	s_cbranch_scc1 .LBB0_484
	v_lshrrev_b32_e32 v0, 3, v226
	v_or_b32_e32 v0, s15, v0
	v_mov_b32_e32 v1, v96
	v_lshlrev_b64 v[0:1], s8, v[0:1]
	s_or_b32 s2, s0, s77
	s_mov_b32 s3, s1
	v_lshl_add_u64 v[0:1], s[2:3], 0, v[0:1]
	s_movk_i32 s4, 0x1800
	v_mov_b64_e32 v[2:3], s[78:79]
	v_mad_u64_u32 v[2:3], s[2:3], v0, s4, v[2:3]
	v_mov_b32_e32 v0, v3
	v_mad_u64_u32 v[0:1], s[2:3], v1, s4, v[0:1]
	v_mov_b32_e32 v3, v0
	s_lshl_b32 s2, s92, 7
	s_mov_b32 s3, s9
	v_lshl_add_u64 v[0:1], v[2:3], 0, s[2:3]
	v_mov_b32_e32 v181, v96
	v_lshl_add_u64 v[0:1], v[0:1], 0, v[180:181]
	v_add_co_u32_e32 v0, vcc, 0x1000, v0
	s_nop 1
	v_addc_co_u32_e32 v1, vcc, 0, v1, vcc
	global_load_dwordx4 v[96:99], v[0:1], off
	global_load_dwordx4 v[100:103], v[0:1], off offset:1024
	s_branch .LBB0_485

.LBB0_912:
	v_lshlrev_b32_e32 v0, 2, v227
	global_load_dword v6, v0, s[84:85]
	global_load_dword v7, v0, s[86:87]
	s_waitcnt vmcnt(0) lgkmcnt(0)
	v_and_b32_e32 v6, 0x7fffffff, v6
	v_and_b32_e32 v7, 0x7fffffff, v7
	s_nop 1
	v_max_f32_dpp v6, v6, v6 quad_perm:[1,0,3,2] row_mask:0xf bank_mask:0xf
	v_max_f32_dpp v7, v7, v7 quad_perm:[1,0,3,2] row_mask:0xf bank_mask:0xf
	s_nop 1
	v_max_f32_dpp v6, v6, v6 quad_perm:[2,3,0,1] row_mask:0xf bank_mask:0xf
	v_max_f32_dpp v7, v7, v7 quad_perm:[2,3,0,1] row_mask:0xf bank_mask:0xf
	s_nop 1
	v_max_f32_dpp v6, v6, v6 row_half_mirror row_mask:0xf bank_mask:0xf
	v_max_f32_dpp v7, v7, v7 row_half_mirror row_mask:0xf bank_mask:0xf
	s_nop 1
	v_max_f32_dpp v6, v6, v6 row_mirror row_mask:0xf bank_mask:0xf
	v_max_f32_dpp v7, v7, v7 row_mirror row_mask:0xf bank_mask:0xf
	s_nop 1
	v_readlane_b32 s0, v6, 0
	v_readlane_b32 s1, v6, 16
	v_readlane_b32 s2, v6, 32
	v_readlane_b32 s3, v6, 48
	s_max_u32 s0, s0, s1
	s_max_u32 s2, s2, s3
	s_max_u32 s0, s0, s2
	v_readlane_b32 s1, v7, 0
	v_readlane_b32 s2, v7, 16
	v_readlane_b32 s3, v7, 32
	v_readlane_b32 s98, v7, 48
	s_max_u32 s1, s1, s2
	s_max_u32 s3, s3, s98
	s_max_u32 s1, s1, s3
	s_nop 0
	v_mov_b32_e32 v6, s0
	v_mov_b32_e32 v7, s1
	s_lshl_b32 s0, s40, 2
	s_and_b32 s6, s0, 60
	s_add_u32 s0, s96, 0x5500000
	s_addc_u32 s1, s97, 0
	s_lshr_b32 s2, s88, 6
	s_lshl_b32 s8, s6, 6
	s_mov_b32 s3, 0
	s_lshl_b64 s[4:5], s[2:3], 12
	s_add_i32 s9, s8, 0xffffff80
	s_lshl_b32 s2, s52, 7
	s_add_u32 s2, s0, s2
	v_and_b32_e32 v0, 56, v230
	s_addc_u32 s3, s1, 0
	v_mov_b32_e32 v1, 0
	v_lshlrev_b32_e32 v0, 1, v0
	s_cmp_eq_u32 s6, 0
	v_lshl_add_u64 v[2:3], s[2:3], 0, v[0:1]
	s_cbranch_scc1 .LBB0_916
	v_or_b32_e32 v4, s9, v205
	v_mov_b32_e32 v5, v1
	v_lshl_add_u64 v[4:5], s[4:5], 0, v[4:5]
	s_movk_i32 s6, 0xc00
	v_mad_u64_u32 v[8:9], s[2:3], v4, s6, v[2:3]
	v_mad_u32_u24 v9, v5, s6, v9
	global_load_dwordx4 v[100:103], v[8:9], off offset:2048
	global_load_dwordx4 v[104:107], v[8:9], off offset:2560
	s_branch .LBB0_917
